# FFN-in epilogue stores the H tile with the nt policy
# baseline (speedup 1.0000x reference)
; __device__ __forceinline__ float row_rstd(const float* ssp, int row, int fq) {
;     const f32x4 t = *((const f32x4*)(ssp + (size_t)row * 16) + fq); float s = (t[0] + t[1]) + (t[2] + t[3]); s += __shfl_xor(s, 16); s += __shfl_xor(s, 32); return rsqrtf(s * (1.0f / DM) + EPS); }
;     __device__ __forceinline__ void operator()(const f32x4 (&acc)[2][2][4][2], const Unit& u, int wr, int wc, int fr, int fq) const {
;     ...
;         float rx[2][4];
; #pragma unroll
;         for (int ai = 0; ai < 2; ++ai)
; #pragma unroll
;             for (int m = 0; m < 4; ++m) rx[ai][m] = row_rstd(ssp, row0 + ai * HALF + m * 16, fq);
; #pragma unroll
;         for (int ai = 0; ai < 2; ++ai)
; #pragma unroll
;             for (int m = 0; m < 4; ++m) { f32x4 o[2];
; #pragma unroll
;                 for (int n = 0; n < 2; ++n) { const f32x4 a = acc[ai][0][m][n] * rx[ai][m], b = acc[ai][1][m][n] * rx[ai][m];
.LBB0_580:
	v_and_b32_e32 v129, 64, v229
	v_xor_b32_e32 v128, 16, v229
	v_add_u32_e32 v129, 64, v129
	v_cmp_lt_i32_e32 vcc, v128, v129
	v_lshl_add_u32 v130, s42, 8, v147
	v_ashrrev_i32_e32 v131, 31, v130
	v_cndmask_b32_e32 v128, v229, v128, vcc
	v_lshlrev_b32_e32 v162, 2, v128
	v_xor_b32_e32 v128, 32, v229
	v_cmp_lt_i32_e32 vcc, v128, v129
	s_mov_b32 s4, 0x358637bd
	s_ashr_i32 s29, s42, 4
	v_cndmask_b32_e32 v128, v229, v128, vcc
	v_lshlrev_b32_e32 v157, 2, v128
	v_lshlrev_b64 v[128:129], 6, v[130:131]
	v_lshl_add_u64 v[128:129], v[140:141], 0, v[128:129]
	global_load_dwordx4 v[170:173], v[128:129], off
	global_load_dwordx4 v[174:177], v[128:129], off offset:1024
	global_load_dwordx4 v[178:181], v[128:129], off offset:2048
	global_load_dwordx4 v[182:185], v[128:129], off offset:3072
	v_add_co_u32_e32 v206, vcc, s82, v128
	s_nop 1
	v_addc_co_u32_e32 v207, vcc, 0, v129, vcc
	global_load_dwordx4 v[186:189], v[206:207], off
	global_load_dwordx4 v[194:197], v[206:207], off offset:1024
	global_load_dwordx4 v[198:201], v[206:207], off offset:2048
	global_load_dwordx4 v[202:205], v[206:207], off offset:3072
	v_and_b32_e32 v155, 0xfcf, v130
	s_mul_hi_i32 s27, s29, 0x1c00000
	s_mul_i32 s29, s29, 0x1c00000
	s_add_u32 s10, s56, s29
	s_addc_u32 s11, s57, s27
	s_waitcnt vmcnt(7)
	v_mov_b32_e32 v164, v171
	v_mov_b32_e32 v165, v172
	v_mov_b32_e32 v171, v173
	v_pk_add_f32 v[164:165], v[164:165], v[170:171]
	s_waitcnt vmcnt(6)
	v_mov_b32_e32 v166, v175
	v_mov_b32_e32 v167, v176
	v_mov_b32_e32 v175, v177
	v_pk_add_f32 v[158:159], v[166:167], v[174:175]
	v_mov_b32_e32 v161, v164
	v_mov_b32_e32 v160, v158
	v_mov_b32_e32 v164, v159
	v_pk_add_f32 v[158:159], v[160:161], v[164:165]
	ds_bpermute_b32 v161, v162, v159
	ds_bpermute_b32 v160, v162, v158
	s_waitcnt lgkmcnt(0)
	v_pk_add_f32 v[158:159], v[158:159], v[160:161]
	ds_bpermute_b32 v161, v157, v159
	ds_bpermute_b32 v160, v157, v158
	s_waitcnt lgkmcnt(0)
	v_pk_add_f32 v[160:161], v[158:159], v[160:161]
	v_mov_b64_e32 v[158:159], s[4:5]
	v_pk_fma_f32 v[160:161], v[160:161], s[38:39], v[158:159] op_sel_hi:[1,0,0]
	s_nop 0
	v_mul_f32_e32 v131, 0x4b800000, v161
	v_cmp_gt_f32_e64 s[42:43], s99, v161
	v_cmp_gt_f32_e32 vcc, s99, v160
	s_nop 0
	v_cndmask_b32_e64 v131, v161, v131, s[42:43]
	v_rsq_f32_e32 v131, v131
	s_nop 0
	v_mul_f32_e32 v146, 0x45800000, v131
	v_cndmask_b32_e64 v156, v131, v146, s[42:43]
	v_mul_f32_e32 v131, 0x4b800000, v160
	v_cndmask_b32_e32 v131, v160, v131, vcc
	v_rsq_f32_e32 v131, v131
	v_pk_mul_f32 v[124:125], v[124:125], v[156:157] op_sel_hi:[1,0]
	v_pk_mul_f32 v[120:121], v[120:121], v[156:157] op_sel_hi:[1,0]
	v_mul_f32_e32 v146, 0x45800000, v131
	v_cndmask_b32_e32 v154, v131, v146, vcc
	v_pk_mul_f32 v[122:123], v[122:123], v[156:157] op_sel_hi:[1,0]
	v_pk_mul_f32 v[116:117], v[116:117], v[156:157] op_sel_hi:[1,0]
	v_pk_mul_f32 v[112:113], v[112:113], v[156:157] op_sel_hi:[1,0]
	v_pk_mul_f32 v[114:115], v[114:115], v[156:157] op_sel_hi:[1,0]
	v_pk_mul_f32 v[108:109], v[108:109], v[154:155] op_sel_hi:[1,0]
	v_pk_mul_f32 v[104:105], v[104:105], v[154:155] op_sel_hi:[1,0]
	v_pk_mul_f32 v[106:107], v[106:107], v[154:155] op_sel_hi:[1,0]
	v_pk_mul_f32 v[100:101], v[100:101], v[154:155] op_sel_hi:[1,0]
	v_pk_mul_f32 v[96:97], v[96:97], v[154:155] op_sel_hi:[1,0]
	v_pk_mul_f32 v[98:99], v[98:99], v[154:155] op_sel_hi:[1,0]
	s_waitcnt vmcnt(5)
	v_mov_b32_e32 v160, v179
	v_mov_b32_e32 v161, v180
	v_mov_b32_e32 v179, v181
	v_pk_add_f32 v[160:161], v[160:161], v[178:179]
	s_waitcnt vmcnt(4)
	v_mov_b32_e32 v130, v183
	v_mov_b32_e32 v131, v184
	v_mov_b32_e32 v183, v185
	v_pk_add_f32 v[130:131], v[130:131], v[182:183]
	v_mov_b32_e32 v165, v160
	v_mov_b32_e32 v164, v130
	v_mov_b32_e32 v160, v131
	v_pk_add_f32 v[130:131], v[164:165], v[160:161]
	ds_bpermute_b32 v161, v162, v131
	ds_bpermute_b32 v160, v162, v130
	s_waitcnt lgkmcnt(0)
	v_pk_add_f32 v[130:131], v[130:131], v[160:161]
	ds_bpermute_b32 v161, v157, v131
	ds_bpermute_b32 v160, v157, v130
	s_waitcnt lgkmcnt(0)
	v_pk_add_f32 v[130:131], v[130:131], v[160:161]
	s_nop 0
	v_pk_fma_f32 v[130:131], v[130:131], s[38:39], v[158:159] op_sel_hi:[1,0,0]
	s_nop 0
	v_mul_f32_e32 v146, 0x4b800000, v131
	v_cmp_gt_f32_e64 s[42:43], s99, v131
	v_cmp_gt_f32_e32 vcc, s99, v130
	s_nop 0
	v_cndmask_b32_e64 v131, v131, v146, s[42:43]
	v_rsq_f32_e32 v131, v131
	s_nop 0
	v_mul_f32_e32 v146, 0x45800000, v131
	v_cndmask_b32_e64 v152, v131, v146, s[42:43]
	v_mul_f32_e32 v131, 0x4b800000, v130
	v_cndmask_b32_e32 v130, v130, v131, vcc
	v_rsq_f32_e32 v130, v130
	v_pk_mul_f32 v[92:93], v[92:93], v[152:153] op_sel_hi:[1,0]
	v_pk_mul_f32 v[88:89], v[88:89], v[152:153] op_sel_hi:[1,0]
	v_pk_mul_f32 v[90:91], v[90:91], v[152:153] op_sel_hi:[1,0]
	v_mul_f32_e32 v131, 0x45800000, v130
	v_cndmask_b32_e32 v150, v130, v131, vcc
	v_pk_mul_f32 v[84:85], v[84:85], v[152:153] op_sel_hi:[1,0]
	v_pk_mul_f32 v[80:81], v[80:81], v[152:153] op_sel_hi:[1,0]
	v_pk_mul_f32 v[82:83], v[82:83], v[152:153] op_sel_hi:[1,0]
	v_pk_mul_f32 v[76:77], v[76:77], v[150:151] op_sel_hi:[1,0]
	v_pk_mul_f32 v[72:73], v[72:73], v[150:151] op_sel_hi:[1,0]
	v_pk_mul_f32 v[74:75], v[74:75], v[150:151] op_sel_hi:[1,0]
	v_pk_mul_f32 v[68:69], v[68:69], v[150:151] op_sel_hi:[1,0]
	v_pk_mul_f32 v[64:65], v[64:65], v[150:151] op_sel_hi:[1,0]
	v_pk_mul_f32 v[66:67], v[66:67], v[150:151] op_sel_hi:[1,0]
	s_waitcnt vmcnt(3)
	v_mov_b32_e32 v130, v187
	v_mov_b32_e32 v131, v188
	v_mov_b32_e32 v187, v189
	v_pk_add_f32 v[130:131], v[130:131], v[186:187]
	s_waitcnt vmcnt(2)
; __device__ __forceinline__ u32x4 pack8(const f32x4& a, const f32x4& b) { u32x4 w; w.x = pk2(a[0], a[1]); w.y = pk2(a[2], a[3]); w.z = pk2(b[0], b[1]); w.w = pk2(b[2], b[3]); return w; }
; __device__ __forceinline__ float sigm(float x) { return __builtin_amdgcn_rcpf(1.0f + __builtin_amdgcn_exp2f(x * -1.4426950408889634f)); }
;     __device__ __forceinline__ void operator()(const f32x4 (&acc)[2][2][4][2], const Unit& u, int wr, int wc, int fr, int fq) const {
;     ...
; #pragma unroll
;         for (int ai = 0; ai < 2; ++ai)
; #pragma unroll
;             for (int m = 0; m < 4; ++m) { f32x4 o[2];
; #pragma unroll
;                 for (int n = 0; n < 2; ++n) { const f32x4 a = acc[ai][0][m][n] * rx[ai][m], b = acc[ai][1][m][n] * rx[ai][m];
; #pragma unroll
;                     for (int e = 0; e < 4; ++e) o[n][e] = a[e] * sigm(a[e]) * b[e]; }
;                 *(u32x4*)(H + (size_t)(lrow0 + ai * HALF + m * 16) * DFF + col0) = pack8(o[0], o[1]); asm volatile("" ::: "memory"); }
	v_mov_b32_e32 v160, v195
	v_mov_b32_e32 v161, v196
	v_mov_b32_e32 v195, v197
	v_pk_add_f32 v[160:161], v[160:161], v[194:195]
	v_mov_b32_e32 v165, v130
	v_mov_b32_e32 v164, v160
	v_mov_b32_e32 v130, v161
	v_pk_add_f32 v[130:131], v[164:165], v[130:131]
	ds_bpermute_b32 v161, v162, v131
	ds_bpermute_b32 v160, v162, v130
	s_waitcnt lgkmcnt(0)
	v_pk_add_f32 v[130:131], v[130:131], v[160:161]
	ds_bpermute_b32 v161, v157, v131
	ds_bpermute_b32 v160, v157, v130
	s_waitcnt lgkmcnt(0)
	v_pk_add_f32 v[130:131], v[130:131], v[160:161]
	s_nop 0
	v_pk_fma_f32 v[130:131], v[130:131], s[38:39], v[158:159] op_sel_hi:[1,0,0]
	s_nop 0
	v_mul_f32_e32 v146, 0x4b800000, v131
	v_cmp_gt_f32_e64 s[42:43], s99, v131
	v_cmp_gt_f32_e32 vcc, s99, v130
	s_nop 0
	v_cndmask_b32_e64 v131, v131, v146, s[42:43]
	v_rsq_f32_e32 v131, v131
	s_nop 0
	v_mul_f32_e32 v146, 0x45800000, v131
	v_cndmask_b32_e64 v148, v131, v146, s[42:43]
	v_mul_f32_e32 v131, 0x4b800000, v130
	v_cndmask_b32_e32 v130, v130, v131, vcc
	v_rsq_f32_e32 v130, v130
	v_pk_mul_f32 v[60:61], v[60:61], v[148:149] op_sel_hi:[1,0]
	v_pk_mul_f32 v[56:57], v[56:57], v[148:149] op_sel_hi:[1,0]
	v_pk_mul_f32 v[58:59], v[58:59], v[148:149] op_sel_hi:[1,0]
	v_mul_f32_e32 v131, 0x45800000, v130
	v_cndmask_b32_e32 v146, v130, v131, vcc
	v_pk_mul_f32 v[52:53], v[52:53], v[148:149] op_sel_hi:[1,0]
	v_pk_mul_f32 v[48:49], v[48:49], v[148:149] op_sel_hi:[1,0]
	v_pk_mul_f32 v[50:51], v[50:51], v[148:149] op_sel_hi:[1,0]
	v_pk_mul_f32 v[44:45], v[44:45], v[146:147] op_sel_hi:[1,0]
	v_pk_mul_f32 v[40:41], v[40:41], v[146:147] op_sel_hi:[1,0]
	v_pk_mul_f32 v[42:43], v[42:43], v[146:147] op_sel_hi:[1,0]
	v_pk_mul_f32 v[36:37], v[36:37], v[146:147] op_sel_hi:[1,0]
	v_pk_mul_f32 v[32:33], v[32:33], v[146:147] op_sel_hi:[1,0]
	v_pk_mul_f32 v[34:35], v[34:35], v[146:147] op_sel_hi:[1,0]
	s_waitcnt vmcnt(1)
	v_mov_b32_e32 v130, v199
	v_mov_b32_e32 v131, v200
	v_mov_b32_e32 v199, v201
	v_pk_add_f32 v[160:161], v[130:131], v[198:199]
	s_waitcnt vmcnt(0)
	v_mov_b32_e32 v164, v203
	v_mov_b32_e32 v165, v204
	v_mov_b32_e32 v203, v205
	v_pk_add_f32 v[128:129], v[164:165], v[202:203]
	v_mov_b32_e32 v131, v160
	v_mov_b32_e32 v130, v128
	v_mov_b32_e32 v160, v129
	v_pk_add_f32 v[128:129], v[130:131], v[160:161]
	ds_bpermute_b32 v131, v162, v129
	ds_bpermute_b32 v130, v162, v128
	s_waitcnt lgkmcnt(0)
	v_pk_add_f32 v[128:129], v[128:129], v[130:131]
	ds_bpermute_b32 v131, v157, v129
	ds_bpermute_b32 v130, v157, v128
	s_waitcnt lgkmcnt(0)
	v_pk_add_f32 v[128:129], v[128:129], v[130:131]
	s_nop 0
	v_pk_fma_f32 v[128:129], v[128:129], s[38:39], v[158:159] op_sel_hi:[1,0,0]
	v_lshl_or_b32 v158, s59, 7, v151
	v_mul_f32_e32 v130, 0x4b800000, v129
	v_cmp_gt_f32_e64 s[42:43], s99, v129
	v_cmp_gt_f32_e32 vcc, s99, v128
	v_ashrrev_i32_e32 v159, 31, v158
	v_cndmask_b32_e64 v129, v129, v130, s[42:43]
	v_rsq_f32_e32 v129, v129
	v_lshl_add_u64 v[158:159], v[158:159], 1, s[10:11]
	v_mul_f32_e32 v130, 0x45800000, v129
	v_cndmask_b32_e64 v130, v129, v130, s[42:43]
	v_mul_f32_e32 v129, 0x4b800000, v128
	v_cndmask_b32_e32 v128, v128, v129, vcc
	v_rsq_f32_e32 v128, v128
	v_pk_mul_f32 v[28:29], v[28:29], v[130:131] op_sel_hi:[1,0]
	v_pk_mul_f32 v[24:25], v[24:25], v[130:131] op_sel_hi:[1,0]
	v_pk_mul_f32 v[26:27], v[26:27], v[130:131] op_sel_hi:[1,0]
	v_mul_f32_e32 v129, 0x45800000, v128
	v_cndmask_b32_e32 v128, v128, v129, vcc
	v_mul_f32_e32 v129, 0xbfb8aa3b, v124
	v_exp_f32_e32 v129, v129
	v_pk_mul_f32 v[20:21], v[20:21], v[130:131] op_sel_hi:[1,0]
	v_pk_mul_f32 v[16:17], v[16:17], v[130:131] op_sel_hi:[1,0]
	v_pk_mul_f32 v[18:19], v[18:19], v[130:131] op_sel_hi:[1,0]
	v_add_f32_e32 v129, 1.0, v129
	v_rcp_f32_e32 v160, v129
	v_mul_f32_e32 v129, 0xbfb8aa3b, v125
	v_exp_f32_e32 v129, v129
	s_mov_b64 s[42:43], -1
	v_add_f32_e32 v129, 1.0, v129
	v_rcp_f32_e32 v161, v129
	v_pk_mul_f32 v[12:13], v[12:13], v[128:129] op_sel_hi:[1,0]
	v_pk_mul_f32 v[8:9], v[8:9], v[128:129] op_sel_hi:[1,0]
	v_pk_mul_f32 v[10:11], v[10:11], v[128:129] op_sel_hi:[1,0]
	v_pk_mul_f32 v[124:125], v[124:125], v[160:161]
	v_pk_mul_f32 v[4:5], v[4:5], v[128:129] op_sel_hi:[1,0]
	v_pk_mul_f32 v[120:121], v[120:121], v[124:125]
	v_pk_mul_f32 v[124:125], v[126:127], v[156:157] op_sel_hi:[1,0]
	v_pk_mul_f32 v[0:1], v[0:1], v[128:129] op_sel_hi:[1,0]
	v_mul_f32_e32 v126, 0xbfb8aa3b, v124
	v_mul_f32_e32 v127, 0xbfb8aa3b, v125
	v_exp_f32_e32 v126, v126
	v_exp_f32_e32 v127, v127
	v_pk_mul_f32 v[2:3], v[2:3], v[128:129] op_sel_hi:[1,0]
	v_add_f32_e32 v126, 1.0, v126
	v_add_f32_e32 v127, 1.0, v127
	v_rcp_f32_e32 v126, v126
	v_rcp_f32_e32 v127, v127
	s_nop 0
	v_pk_mul_f32 v[124:125], v[124:125], v[126:127]
	s_nop 0
	v_pk_mul_f32 v[122:123], v[122:123], v[124:125]
	v_mul_f32_e32 v124, 0xbfb8aa3b, v116
	v_mul_f32_e32 v125, 0xbfb8aa3b, v117
	v_exp_f32_e32 v124, v124
	v_exp_f32_e32 v125, v125
	v_add_f32_e32 v124, 1.0, v124
	v_add_f32_e32 v125, 1.0, v125
	v_rcp_f32_e32 v124, v124
	v_rcp_f32_e32 v125, v125
	s_nop 0
	v_pk_mul_f32 v[116:117], v[116:117], v[124:125]
	s_nop 0
	v_pk_mul_f32 v[112:113], v[112:113], v[116:117]
	v_pk_mul_f32 v[116:117], v[118:119], v[156:157] op_sel_hi:[1,0]
	s_nop 0
	v_mul_f32_e32 v118, 0xbfb8aa3b, v116
	v_mul_f32_e32 v119, 0xbfb8aa3b, v117
	v_exp_f32_e32 v118, v118
	v_exp_f32_e32 v119, v119
	v_add_f32_e32 v118, 1.0, v118
	v_add_f32_e32 v119, 1.0, v119
	v_rcp_f32_e32 v118, v118
	v_rcp_f32_e32 v119, v119
	s_nop 0
	v_pk_mul_f32 v[116:117], v[116:117], v[118:119]
	s_nop 0
	v_pk_mul_f32 v[118:119], v[114:115], v[116:117]
	v_cvt_pk_bf16_f32 v116, v112, v113
	v_mul_u32_u24_e32 v112, 0xb00, v155
	v_lshlrev_b32_e32 v192, 1, v112
	v_cvt_pk_bf16_f32 v114, v120, v121
	v_cvt_pk_bf16_f32 v115, v122, v123
; __device__ __forceinline__ u32x4 pack8(const f32x4& a, const f32x4& b) { u32x4 w; w.x = pk2(a[0], a[1]); w.y = pk2(a[2], a[3]); w.z = pk2(b[0], b[1]); w.w = pk2(b[2], b[3]); return w; }
; __device__ __forceinline__ float sigm(float x) { return __builtin_amdgcn_rcpf(1.0f + __builtin_amdgcn_exp2f(x * -1.4426950408889634f)); }
;     __device__ __forceinline__ void operator()(const f32x4 (&acc)[2][2][4][2], const Unit& u, int wr, int wc, int fr, int fq) const {
;     ...
; #pragma unroll
;         for (int ai = 0; ai < 2; ++ai)
; #pragma unroll
;             for (int m = 0; m < 4; ++m) { f32x4 o[2];
; #pragma unroll
;                 for (int n = 0; n < 2; ++n) { const f32x4 a = acc[ai][0][m][n] * rx[ai][m], b = acc[ai][1][m][n] * rx[ai][m];
; #pragma unroll
;                     for (int e = 0; e < 4; ++e) o[n][e] = a[e] * sigm(a[e]) * b[e]; }
;                 *(u32x4*)(H + (size_t)(lrow0 + ai * HALF + m * 16) * DFF + col0) = pack8(o[0], o[1]); asm volatile("" ::: "memory"); }
	v_cvt_pk_bf16_f32 v117, v118, v119
	v_lshl_add_u64 v[112:113], v[158:159], 0, v[192:193]
	global_store_dwordx4 v[112:113], v[114:117], off nt
	s_nop 1
	v_mul_f32_e32 v114, 0xbfb8aa3b, v108
	v_mul_f32_e32 v115, 0xbfb8aa3b, v109
	v_exp_f32_e32 v114, v114
	v_exp_f32_e32 v115, v115
	v_add_f32_e32 v114, 1.0, v114
	v_add_f32_e32 v115, 1.0, v115
	v_rcp_f32_e32 v114, v114
	v_rcp_f32_e32 v115, v115
	s_nop 0
	v_pk_mul_f32 v[108:109], v[108:109], v[114:115]
	s_nop 0
	v_pk_mul_f32 v[104:105], v[104:105], v[108:109]
	v_pk_mul_f32 v[108:109], v[110:111], v[154:155] op_sel_hi:[1,0]
	s_nop 0
	v_mul_f32_e32 v110, 0xbfb8aa3b, v108
	v_mul_f32_e32 v111, 0xbfb8aa3b, v109
	v_exp_f32_e32 v110, v110
	v_exp_f32_e32 v111, v111
	v_add_f32_e32 v110, 1.0, v110
	v_add_f32_e32 v111, 1.0, v111
	v_rcp_f32_e32 v110, v110
	v_rcp_f32_e32 v111, v111
	s_nop 0
	v_pk_mul_f32 v[108:109], v[108:109], v[110:111]
	s_nop 0
	v_pk_mul_f32 v[106:107], v[106:107], v[108:109]
	v_mul_f32_e32 v108, 0xbfb8aa3b, v100
	v_mul_f32_e32 v109, 0xbfb8aa3b, v101
	v_exp_f32_e32 v108, v108
	v_exp_f32_e32 v109, v109
	v_add_f32_e32 v108, 1.0, v108
	v_add_f32_e32 v109, 1.0, v109
	v_rcp_f32_e32 v108, v108
	v_rcp_f32_e32 v109, v109
	s_nop 0
	v_pk_mul_f32 v[100:101], v[100:101], v[108:109]
	s_nop 0
	v_pk_mul_f32 v[100:101], v[96:97], v[100:101]
	v_pk_mul_f32 v[96:97], v[102:103], v[154:155] op_sel_hi:[1,0]
	s_nop 0
	v_mul_f32_e32 v102, 0xbfb8aa3b, v96
	v_mul_f32_e32 v103, 0xbfb8aa3b, v97
	v_exp_f32_e32 v102, v102
	v_exp_f32_e32 v103, v103
	v_add_f32_e32 v102, 1.0, v102
	v_add_f32_e32 v103, 1.0, v103
	v_rcp_f32_e32 v102, v102
	v_rcp_f32_e32 v103, v103
	s_nop 0
	v_pk_mul_f32 v[96:97], v[96:97], v[102:103]
	s_nop 0
	v_pk_mul_f32 v[102:103], v[98:99], v[96:97]
	v_cvt_pk_bf16_f32 v98, v100, v101
	v_add_co_u32_e32 v100, vcc, s69, v112
	v_cvt_pk_bf16_f32 v96, v104, v105
	v_cvt_pk_bf16_f32 v97, v106, v107
	v_cvt_pk_bf16_f32 v99, v102, v103
	v_addc_co_u32_e32 v101, vcc, 0, v113, vcc
	global_store_dwordx4 v[100:101], v[96:99], off nt
	s_nop 1
	v_mul_f32_e32 v96, 0xbfb8aa3b, v92
	v_mul_f32_e32 v97, 0xbfb8aa3b, v93
	v_exp_f32_e32 v96, v96
	v_exp_f32_e32 v97, v97
	v_add_f32_e32 v96, 1.0, v96
	v_add_f32_e32 v97, 1.0, v97
	v_rcp_f32_e32 v96, v96
	v_rcp_f32_e32 v97, v97
	s_nop 0
	v_pk_mul_f32 v[92:93], v[92:93], v[96:97]
	s_nop 0
	v_pk_mul_f32 v[88:89], v[88:89], v[92:93]
	v_pk_mul_f32 v[92:93], v[94:95], v[152:153] op_sel_hi:[1,0]
	s_nop 0
	v_mul_f32_e32 v94, 0xbfb8aa3b, v92
	v_mul_f32_e32 v95, 0xbfb8aa3b, v93
	v_exp_f32_e32 v94, v94
	v_exp_f32_e32 v95, v95
	v_add_f32_e32 v94, 1.0, v94
	v_add_f32_e32 v95, 1.0, v95
	v_rcp_f32_e32 v94, v94
	v_rcp_f32_e32 v95, v95
	s_nop 0
	v_pk_mul_f32 v[92:93], v[92:93], v[94:95]
	s_nop 0
	v_pk_mul_f32 v[90:91], v[90:91], v[92:93]
	v_mul_f32_e32 v92, 0xbfb8aa3b, v84
	v_mul_f32_e32 v93, 0xbfb8aa3b, v85
	v_exp_f32_e32 v92, v92
	v_exp_f32_e32 v93, v93
	v_add_f32_e32 v92, 1.0, v92
	v_add_f32_e32 v93, 1.0, v93
	v_rcp_f32_e32 v92, v92
	v_rcp_f32_e32 v93, v93
	s_nop 0
	v_pk_mul_f32 v[84:85], v[84:85], v[92:93]
	s_nop 0
	v_pk_mul_f32 v[84:85], v[80:81], v[84:85]
	v_pk_mul_f32 v[80:81], v[86:87], v[152:153] op_sel_hi:[1,0]
	s_nop 0
	v_mul_f32_e32 v86, 0xbfb8aa3b, v80
	v_mul_f32_e32 v87, 0xbfb8aa3b, v81
	v_exp_f32_e32 v86, v86
	v_exp_f32_e32 v87, v87
	v_add_f32_e32 v86, 1.0, v86
	v_add_f32_e32 v87, 1.0, v87
	v_rcp_f32_e32 v86, v86
	v_rcp_f32_e32 v87, v87
	s_nop 0
	v_pk_mul_f32 v[80:81], v[80:81], v[86:87]
	s_nop 0
	v_pk_mul_f32 v[86:87], v[82:83], v[80:81]
	v_cvt_pk_bf16_f32 v82, v84, v85
	v_add_co_u32_e32 v84, vcc, s73, v112
	v_cvt_pk_bf16_f32 v80, v88, v89
	v_cvt_pk_bf16_f32 v81, v90, v91
	v_cvt_pk_bf16_f32 v83, v86, v87
	v_addc_co_u32_e32 v85, vcc, 0, v113, vcc
	global_store_dwordx4 v[84:85], v[80:83], off nt
	s_nop 1
	v_mul_f32_e32 v80, 0xbfb8aa3b, v76
	v_mul_f32_e32 v81, 0xbfb8aa3b, v77
	v_exp_f32_e32 v80, v80
	v_exp_f32_e32 v81, v81
	v_add_f32_e32 v80, 1.0, v80
	v_add_f32_e32 v81, 1.0, v81
	v_rcp_f32_e32 v80, v80
	v_rcp_f32_e32 v81, v81
	s_nop 0
	v_pk_mul_f32 v[76:77], v[76:77], v[80:81]
	s_nop 0
	v_pk_mul_f32 v[72:73], v[72:73], v[76:77]
	v_pk_mul_f32 v[76:77], v[78:79], v[150:151] op_sel_hi:[1,0]
	s_nop 0
	v_mul_f32_e32 v78, 0xbfb8aa3b, v76
	v_mul_f32_e32 v79, 0xbfb8aa3b, v77
	v_exp_f32_e32 v78, v78
	v_exp_f32_e32 v79, v79
	v_add_f32_e32 v78, 1.0, v78
	v_add_f32_e32 v79, 1.0, v79
	v_rcp_f32_e32 v78, v78
	v_rcp_f32_e32 v79, v79
	s_nop 0
	v_pk_mul_f32 v[76:77], v[76:77], v[78:79]
	s_nop 0
	v_pk_mul_f32 v[74:75], v[74:75], v[76:77]
	v_mul_f32_e32 v76, 0xbfb8aa3b, v68
	v_mul_f32_e32 v77, 0xbfb8aa3b, v69
	v_exp_f32_e32 v76, v76
	v_exp_f32_e32 v77, v77
	v_add_f32_e32 v76, 1.0, v76
	v_add_f32_e32 v77, 1.0, v77
	v_rcp_f32_e32 v76, v76
	v_rcp_f32_e32 v77, v77
	s_nop 0
	v_pk_mul_f32 v[68:69], v[68:69], v[76:77]
	s_nop 0
	v_pk_mul_f32 v[68:69], v[64:65], v[68:69]
	v_pk_mul_f32 v[64:65], v[70:71], v[150:151] op_sel_hi:[1,0]
	s_nop 0
	v_mul_f32_e32 v70, 0xbfb8aa3b, v64
	v_mul_f32_e32 v71, 0xbfb8aa3b, v65
	v_exp_f32_e32 v70, v70
	v_exp_f32_e32 v71, v71
	v_add_f32_e32 v70, 1.0, v70
	v_add_f32_e32 v71, 1.0, v71
	v_rcp_f32_e32 v70, v70
	v_rcp_f32_e32 v71, v71
	s_nop 0
	v_pk_mul_f32 v[64:65], v[64:65], v[70:71]
	s_nop 0
	v_pk_mul_f32 v[70:71], v[66:67], v[64:65]
	v_cvt_pk_bf16_f32 v66, v68, v69
	v_add_co_u32_e32 v68, vcc, s74, v112
	v_cvt_pk_bf16_f32 v64, v72, v73
	v_cvt_pk_bf16_f32 v65, v74, v75
	v_cvt_pk_bf16_f32 v67, v70, v71
	v_addc_co_u32_e32 v69, vcc, 0, v113, vcc
	global_store_dwordx4 v[68:69], v[64:67], off nt
	s_nop 1
	v_mul_f32_e32 v64, 0xbfb8aa3b, v60
	v_mul_f32_e32 v65, 0xbfb8aa3b, v61
	v_exp_f32_e32 v64, v64
	v_exp_f32_e32 v65, v65
	v_add_f32_e32 v64, 1.0, v64
	v_add_f32_e32 v65, 1.0, v65
; __device__ __forceinline__ u32x4 pack8(const f32x4& a, const f32x4& b) { u32x4 w; w.x = pk2(a[0], a[1]); w.y = pk2(a[2], a[3]); w.z = pk2(b[0], b[1]); w.w = pk2(b[2], b[3]); return w; }
; __device__ __forceinline__ float sigm(float x) { return __builtin_amdgcn_rcpf(1.0f + __builtin_amdgcn_exp2f(x * -1.4426950408889634f)); }
;     __device__ __forceinline__ void operator()(const f32x4 (&acc)[2][2][4][2], const Unit& u, int wr, int wc, int fr, int fq) const {
;     ...
; #pragma unroll
;         for (int ai = 0; ai < 2; ++ai)
; #pragma unroll
;             for (int m = 0; m < 4; ++m) { f32x4 o[2];
; #pragma unroll
;                 for (int n = 0; n < 2; ++n) { const f32x4 a = acc[ai][0][m][n] * rx[ai][m], b = acc[ai][1][m][n] * rx[ai][m];
; #pragma unroll
;                     for (int e = 0; e < 4; ++e) o[n][e] = a[e] * sigm(a[e]) * b[e]; }
;                 *(u32x4*)(H + (size_t)(lrow0 + ai * HALF + m * 16) * DFF + col0) = pack8(o[0], o[1]); asm volatile("" ::: "memory"); }
	v_rcp_f32_e32 v64, v64
	v_rcp_f32_e32 v65, v65
	s_nop 0
	v_pk_mul_f32 v[60:61], v[60:61], v[64:65]
	s_nop 0
	v_pk_mul_f32 v[56:57], v[56:57], v[60:61]
	v_pk_mul_f32 v[60:61], v[62:63], v[148:149] op_sel_hi:[1,0]
	s_nop 0
	v_mul_f32_e32 v62, 0xbfb8aa3b, v60
	v_mul_f32_e32 v63, 0xbfb8aa3b, v61
	v_exp_f32_e32 v62, v62
	v_exp_f32_e32 v63, v63
	v_add_f32_e32 v62, 1.0, v62
	v_add_f32_e32 v63, 1.0, v63
	v_rcp_f32_e32 v62, v62
	v_rcp_f32_e32 v63, v63
	s_nop 0
	v_pk_mul_f32 v[60:61], v[60:61], v[62:63]
	s_nop 0
	v_pk_mul_f32 v[58:59], v[58:59], v[60:61]
	v_mul_f32_e32 v60, 0xbfb8aa3b, v52
	v_mul_f32_e32 v61, 0xbfb8aa3b, v53
	v_exp_f32_e32 v60, v60
	v_exp_f32_e32 v61, v61
	v_add_f32_e32 v60, 1.0, v60
	v_add_f32_e32 v61, 1.0, v61
	v_rcp_f32_e32 v60, v60
	v_rcp_f32_e32 v61, v61
	s_nop 0
	v_pk_mul_f32 v[52:53], v[52:53], v[60:61]
	s_nop 0
	v_pk_mul_f32 v[52:53], v[48:49], v[52:53]
	v_pk_mul_f32 v[48:49], v[54:55], v[148:149] op_sel_hi:[1,0]
	s_nop 0
	v_mul_f32_e32 v54, 0xbfb8aa3b, v48
	v_mul_f32_e32 v55, 0xbfb8aa3b, v49
	v_exp_f32_e32 v54, v54
	v_exp_f32_e32 v55, v55
	v_add_f32_e32 v54, 1.0, v54
	v_add_f32_e32 v55, 1.0, v55
	v_rcp_f32_e32 v54, v54
	v_rcp_f32_e32 v55, v55
	s_nop 0
	v_pk_mul_f32 v[48:49], v[48:49], v[54:55]
	s_nop 0
	v_pk_mul_f32 v[54:55], v[50:51], v[48:49]
	v_cvt_pk_bf16_f32 v50, v52, v53
	v_add_co_u32_e32 v52, vcc, s75, v112
	v_cvt_pk_bf16_f32 v48, v56, v57
	v_cvt_pk_bf16_f32 v49, v58, v59
	v_cvt_pk_bf16_f32 v51, v54, v55
	v_addc_co_u32_e32 v53, vcc, 0, v113, vcc
	global_store_dwordx4 v[52:53], v[48:51], off nt
	s_nop 1
	v_mul_f32_e32 v48, 0xbfb8aa3b, v44
	v_mul_f32_e32 v49, 0xbfb8aa3b, v45
	v_exp_f32_e32 v48, v48
	v_exp_f32_e32 v49, v49
	v_add_f32_e32 v48, 1.0, v48
	v_add_f32_e32 v49, 1.0, v49
	v_rcp_f32_e32 v48, v48
	v_rcp_f32_e32 v49, v49
	s_nop 0
	v_pk_mul_f32 v[44:45], v[44:45], v[48:49]
	s_nop 0
	v_pk_mul_f32 v[40:41], v[40:41], v[44:45]
	v_pk_mul_f32 v[44:45], v[46:47], v[146:147] op_sel_hi:[1,0]
	s_nop 0
	v_mul_f32_e32 v46, 0xbfb8aa3b, v44
	v_mul_f32_e32 v47, 0xbfb8aa3b, v45
	v_exp_f32_e32 v46, v46
	v_exp_f32_e32 v47, v47
	v_add_f32_e32 v46, 1.0, v46
	v_add_f32_e32 v47, 1.0, v47
	v_rcp_f32_e32 v46, v46
	v_rcp_f32_e32 v47, v47
	s_nop 0
	v_pk_mul_f32 v[44:45], v[44:45], v[46:47]
	s_nop 0
	v_pk_mul_f32 v[42:43], v[42:43], v[44:45]
	v_mul_f32_e32 v44, 0xbfb8aa3b, v36
	v_mul_f32_e32 v45, 0xbfb8aa3b, v37
	v_exp_f32_e32 v44, v44
	v_exp_f32_e32 v45, v45
	v_add_f32_e32 v44, 1.0, v44
	v_add_f32_e32 v45, 1.0, v45
	v_rcp_f32_e32 v44, v44
	v_rcp_f32_e32 v45, v45
	s_nop 0
	v_pk_mul_f32 v[36:37], v[36:37], v[44:45]
	s_nop 0
	v_pk_mul_f32 v[36:37], v[32:33], v[36:37]
	v_pk_mul_f32 v[32:33], v[38:39], v[146:147] op_sel_hi:[1,0]
	s_nop 0
	v_mul_f32_e32 v38, 0xbfb8aa3b, v32
	v_mul_f32_e32 v39, 0xbfb8aa3b, v33
	v_exp_f32_e32 v38, v38
	v_exp_f32_e32 v39, v39
	v_add_f32_e32 v38, 1.0, v38
	v_add_f32_e32 v39, 1.0, v39
	v_rcp_f32_e32 v38, v38
	v_rcp_f32_e32 v39, v39
	s_nop 0
	v_pk_mul_f32 v[32:33], v[32:33], v[38:39]
	s_nop 0
	v_pk_mul_f32 v[38:39], v[34:35], v[32:33]
	v_cvt_pk_bf16_f32 v34, v36, v37
	v_add_co_u32_e32 v36, vcc, s76, v112
	v_cvt_pk_bf16_f32 v32, v40, v41
	v_cvt_pk_bf16_f32 v33, v42, v43
	v_cvt_pk_bf16_f32 v35, v38, v39
	v_addc_co_u32_e32 v37, vcc, 0, v113, vcc
	global_store_dwordx4 v[36:37], v[32:35], off nt
	s_nop 1
	v_mul_f32_e32 v32, 0xbfb8aa3b, v28
	v_mul_f32_e32 v33, 0xbfb8aa3b, v29
	v_exp_f32_e32 v32, v32
	v_exp_f32_e32 v33, v33
	v_add_f32_e32 v32, 1.0, v32
	v_add_f32_e32 v33, 1.0, v33
	v_rcp_f32_e32 v32, v32
	v_rcp_f32_e32 v33, v33
	s_nop 0
	v_pk_mul_f32 v[28:29], v[28:29], v[32:33]
	s_nop 0
	v_pk_mul_f32 v[24:25], v[24:25], v[28:29]
	v_pk_mul_f32 v[28:29], v[30:31], v[130:131] op_sel_hi:[1,0]
	s_nop 0
	v_mul_f32_e32 v30, 0xbfb8aa3b, v28
	v_mul_f32_e32 v31, 0xbfb8aa3b, v29
	v_exp_f32_e32 v30, v30
	v_exp_f32_e32 v31, v31
	v_add_f32_e32 v30, 1.0, v30
	v_add_f32_e32 v31, 1.0, v31
	v_rcp_f32_e32 v30, v30
	v_rcp_f32_e32 v31, v31
	s_nop 0
	v_pk_mul_f32 v[28:29], v[28:29], v[30:31]
	s_nop 0
	v_pk_mul_f32 v[26:27], v[26:27], v[28:29]
	v_mul_f32_e32 v28, 0xbfb8aa3b, v20
	v_mul_f32_e32 v29, 0xbfb8aa3b, v21
	v_exp_f32_e32 v28, v28
	v_exp_f32_e32 v29, v29
	v_add_f32_e32 v28, 1.0, v28
	v_add_f32_e32 v29, 1.0, v29
	v_rcp_f32_e32 v28, v28
	v_rcp_f32_e32 v29, v29
	s_nop 0
	v_pk_mul_f32 v[20:21], v[20:21], v[28:29]
	s_nop 0
	v_pk_mul_f32 v[20:21], v[16:17], v[20:21]
	v_pk_mul_f32 v[16:17], v[22:23], v[130:131] op_sel_hi:[1,0]
	s_nop 0
	v_mul_f32_e32 v22, 0xbfb8aa3b, v16
	v_mul_f32_e32 v23, 0xbfb8aa3b, v17
	v_exp_f32_e32 v22, v22
	v_exp_f32_e32 v23, v23
	v_add_f32_e32 v22, 1.0, v22
	v_add_f32_e32 v23, 1.0, v23
	v_rcp_f32_e32 v22, v22
	v_rcp_f32_e32 v23, v23
	s_nop 0
	v_pk_mul_f32 v[16:17], v[16:17], v[22:23]
	s_nop 0
	v_pk_mul_f32 v[22:23], v[18:19], v[16:17]
	v_cvt_pk_bf16_f32 v18, v20, v21
	v_add_co_u32_e32 v20, vcc, s77, v112
	v_cvt_pk_bf16_f32 v16, v24, v25
	v_cvt_pk_bf16_f32 v17, v26, v27
	v_cvt_pk_bf16_f32 v19, v22, v23
	v_addc_co_u32_e32 v21, vcc, 0, v113, vcc
	global_store_dwordx4 v[20:21], v[16:19], off nt
	s_nop 1
	v_mul_f32_e32 v16, 0xbfb8aa3b, v12
	v_mul_f32_e32 v17, 0xbfb8aa3b, v13
	v_exp_f32_e32 v16, v16
	v_exp_f32_e32 v17, v17
	v_add_f32_e32 v16, 1.0, v16
	v_add_f32_e32 v17, 1.0, v17
	v_rcp_f32_e32 v16, v16
	v_rcp_f32_e32 v17, v17
	s_nop 0
	v_pk_mul_f32 v[12:13], v[12:13], v[16:17]
	s_nop 0
	v_pk_mul_f32 v[8:9], v[8:9], v[12:13]
	v_pk_mul_f32 v[12:13], v[14:15], v[128:129] op_sel_hi:[1,0]
	s_nop 0
	v_mul_f32_e32 v14, 0xbfb8aa3b, v12
	v_mul_f32_e32 v15, 0xbfb8aa3b, v13
	v_exp_f32_e32 v14, v14
	v_exp_f32_e32 v15, v15
	v_add_f32_e32 v14, 1.0, v14
	v_add_f32_e32 v15, 1.0, v15
	v_rcp_f32_e32 v14, v14
	v_rcp_f32_e32 v15, v15
	s_nop 0
	v_pk_mul_f32 v[12:13], v[12:13], v[14:15]
	s_nop 0
	v_pk_mul_f32 v[10:11], v[10:11], v[12:13]
	v_mul_f32_e32 v12, 0xbfb8aa3b, v4
	v_mul_f32_e32 v13, 0xbfb8aa3b, v5
	v_exp_f32_e32 v12, v12
	v_exp_f32_e32 v13, v13
	v_add_f32_e32 v12, 1.0, v12
	v_add_f32_e32 v13, 1.0, v13
	v_rcp_f32_e32 v12, v12
	v_rcp_f32_e32 v13, v13
	s_nop 0
	v_pk_mul_f32 v[4:5], v[4:5], v[12:13]
	s_nop 0
	v_pk_mul_f32 v[4:5], v[0:1], v[4:5]
	v_pk_mul_f32 v[0:1], v[6:7], v[128:129] op_sel_hi:[1,0]
	s_nop 0
	v_mul_f32_e32 v6, 0xbfb8aa3b, v0
	v_mul_f32_e32 v7, 0xbfb8aa3b, v1
	v_exp_f32_e32 v6, v6
	v_exp_f32_e32 v7, v7
	v_add_f32_e32 v6, 1.0, v6
	v_add_f32_e32 v7, 1.0, v7
	v_rcp_f32_e32 v6, v6
	v_rcp_f32_e32 v7, v7
	s_nop 0
	v_pk_mul_f32 v[0:1], v[0:1], v[6:7]
	s_nop 0
	v_pk_mul_f32 v[6:7], v[2:3], v[0:1]
	v_cvt_pk_bf16_f32 v2, v4, v5
	v_add_co_u32_e32 v4, vcc, 0xf2000, v112
	v_cvt_pk_bf16_f32 v0, v8, v9
	v_cvt_pk_bf16_f32 v1, v10, v11
	v_cvt_pk_bf16_f32 v3, v6, v7
	v_addc_co_u32_e32 v5, vcc, 0, v113, vcc
	global_store_dwordx4 v[4:5], v[0:3], off nt
	s_andn2_b64 vcc, exec, s[40:41]
	s_cbranch_vccnz .LBB0_573
	s_andn2_b64 vcc, exec, s[22:23]
	s_cbranch_vccnz .LBB0_572
	s_barrier
	s_branch .LBB0_572
